# no grid barrier between the scan/NA phase and the attention/hgrn phase (scan publish + acquire before hgrn); second-round hgrn items and NA units rebalanced across blocks
# speedup vs baseline: 1.0221x; 1.0194x over previous
; __global__ void __launch_bounds__(512, 2) mk_fwd(Args args) {
;     ...
;                 { const Ctx F = relaunder(F0); attn_phase(F, args, l); }
;                 __syncthreads();
;                 if (PHM & 256) { const Ctx F = relaunder(F0); hgrn_out_phase(F, args, l); }
.LBB0_311:
	v_readfirstlane_b32 s2, v166
	s_cmp_lg_u32 s2, 0
	s_cbranch_scc1 .Lhw_bar
	v_readlane_b32 s2, v253, 17
	s_add_i32 s2, s2, 6
	s_mul_i32 s2, s2, 0x124a
	s_lshr_b32 s2, s2, 16
	s_lshl_b32 s2, s2, 6
	s_add_u32 s22, s14, 0x3900
	s_addc_u32 s23, s15, 0
	s_mov_b64 s[6:7], exec
	s_mov_b64 exec, 1
.Lhw_spin:
	global_load_dword v2, v1, s[22:23] sc1
	s_waitcnt vmcnt(0)
	v_readfirstlane_b32 s3, v2
	s_cmp_lt_u32 s3, s2
	s_cbranch_scc0 .Lhw_got
	s_sleep 1
	s_branch .Lhw_spin
.Lhw_got:
	buffer_inv sc1
	s_waitcnt vmcnt(0)
	s_mov_b64 exec, s[6:7]

; __device__ __forceinline__ float bf2f(unsigned v) { return __uint_as_float(v << 16); }
; __device__ __forceinline__ unsigned f2bf(float f) { return pk2(f, 0.f) & 0xffffu; }
; __device__ __forceinline__ float siluf_(float x) { return x * __builtin_amdgcn_rcpf(1.0f + __builtin_amdgcn_exp2f(-1.4426950408889634f * x)); }
; __device__ __forceinline__ void hgrn_out_phase(const Ctx& F, const Args& a, int l) {
;     ...
; #pragma unroll 4
;             for (int k = 0; k < 32; ++k) {
;                 const int tt = 32 * dir + k;
;                 const float ot = ob_f[tt * 64 + lane] + ob_b[tt * 64 + lane];
;                 const float ss = wave_sum(ot * ot);
;                 const float gg = bf2f(PB[(size_t)(rb + tt) * INW + C_BG + head * 64 + lane]);
;                 const float y = ot * (1.0f / sqrtf(ss * (1.f / 64.f) + EPSN)) * og * siluf_(gg);
;                 Y[(size_t)(rb + tt) * D + 256 + head * 64 + lane] = (bf16_t)f2bf(y);
;             }
.LBB0_314:
	v_add_u32_e32 v4, s6, v0
	v_add_u32_e32 v5, 0x14000, v4
	ds_read2st64_b32 v[2:3], v4 offset0:32 offset1:33
	ds_read_b32 v5, v5
	s_add_i32 s22, s44, -3
	s_ashr_i32 s23, s22, 31
	s_add_i32 s82, s44, -1
	s_ashr_i32 s83, s82, 31
	s_waitcnt lgkmcnt(0)
	v_add_f32_e32 v2, v2, v5
	v_mul_f32_e32 v5, v2, v2
	ds_swizzle_b32 v5, v5 offset:swizzle(SWAP,1)
	s_ashr_i32 s45, s44, 31
	s_addk_i32 s6, 0x400
	s_waitcnt lgkmcnt(0)
	v_fmac_f32_e32 v5, v2, v2
	ds_swizzle_b32 v6, v5 offset:swizzle(SWAP,2)
	s_waitcnt lgkmcnt(0)
	v_add_f32_e32 v5, v5, v6
	ds_swizzle_b32 v6, v5 offset:swizzle(SWAP,4)
	s_waitcnt lgkmcnt(0)
	v_add_f32_e32 v5, v5, v6
	ds_swizzle_b32 v6, v5 offset:swizzle(SWAP,8)
	s_waitcnt lgkmcnt(0)
	v_add_f32_e32 v5, v5, v6
	ds_swizzle_b32 v6, v5 offset:swizzle(SWAP,16)
	s_waitcnt lgkmcnt(0)
	v_add_f32_e32 v5, v5, v6
	v_mov_b32_e32 v6, v5
	s_nop 1
	v_permlane32_swap_b32_e32 v5, v6
	v_add_f32_e32 v5, v5, v6
	v_mad_i64_i32 v[6:7], s[4:5], s22, v205, v[116:117]
	global_load_ushort v6, v[6:7], off offset:3072
	v_fmamk_f32 v5, v5, 0x3c800000, v193
	v_cmp_gt_f32_e32 vcc, s41, v5
	s_waitcnt vmcnt(0)
	v_lshlrev_b32_e32 v7, 16, v6
	v_mul_f32_e32 v6, 0x4f800000, v5
	v_cndmask_b32_e32 v5, v5, v6, vcc
	v_sqrt_f32_e32 v6, v5
	s_nop 0
	v_add_u32_e32 v8, -1, v6
	v_fma_f32 v9, -v8, v6, v5
	v_cmp_ge_f32_e64 s[4:5], 0, v9
	v_add_u32_e32 v9, 1, v6
	s_nop 0
	v_cndmask_b32_e64 v8, v6, v8, s[4:5]
	v_fma_f32 v6, -v9, v6, v5
	v_cmp_lt_f32_e64 s[4:5], 0, v6
	s_nop 1
	v_cndmask_b32_e64 v6, v8, v9, s[4:5]
	v_mul_f32_e32 v8, 0x37800000, v6
	v_cndmask_b32_e32 v6, v6, v8, vcc
	v_cmp_class_f32_e32 vcc, v5, v202
	s_nop 1
	v_cndmask_b32_e32 v5, v6, v5, vcc
	v_div_scale_f32 v6, s[4:5], v5, v5, 1.0
	v_rcp_f32_e32 v8, v6
	s_lshl_b64 s[4:5], s[22:23], 11
	s_add_i32 s22, s44, -2
	s_ashr_i32 s23, s22, 31
	v_fma_f32 v9, -v6, v8, 1.0
	v_fmac_f32_e32 v8, v9, v8
	v_div_scale_f32 v9, vcc, 1.0, v5, 1.0
	v_mul_f32_e32 v10, v9, v8
	v_fma_f32 v11, -v6, v10, v9
	v_fmac_f32_e32 v10, v11, v8
	v_fma_f32 v6, -v6, v10, v9
	v_div_fmas_f32 v6, v6, v8, v10
	v_div_fixup_f32 v5, v6, v5, 1.0
	v_mul_f32_e32 v6, v2, v5
	v_mul_f32_e32 v2, 0xbfb8aa3b, v7
	v_exp_f32_e32 v2, v2
	s_nop 0
	v_add_f32_e32 v2, 1.0, v2
	v_rcp_f32_e32 v99, v2
	s_nop 0
	v_pk_mul_f32 v[6:7], v[98:99], v[6:7]
	s_nop 0
	v_mul_f32_e32 v2, v6, v7
	v_cvt_pk_bf16_f32 v2, v2, s0
	v_lshl_add_u64 v[6:7], v[112:113], 0, s[4:5]
	global_store_short v[6:7], v2, off
	v_add_u32_e32 v2, 0x14100, v4
	ds_read_b32 v2, v2
	s_waitcnt lgkmcnt(0)
	v_add_f32_e32 v5, v3, v2
	v_mul_f32_e32 v2, v5, v5
	ds_swizzle_b32 v2, v2 offset:swizzle(SWAP,1)
	s_waitcnt lgkmcnt(0)
	v_fmac_f32_e32 v2, v5, v5
	ds_swizzle_b32 v3, v2 offset:swizzle(SWAP,2)
	s_waitcnt lgkmcnt(0)
	v_add_f32_e32 v2, v2, v3
	ds_swizzle_b32 v3, v2 offset:swizzle(SWAP,4)
	s_waitcnt lgkmcnt(0)
	v_add_f32_e32 v2, v2, v3
	ds_swizzle_b32 v3, v2 offset:swizzle(SWAP,8)
	s_waitcnt lgkmcnt(0)
	v_add_f32_e32 v2, v2, v3
	ds_swizzle_b32 v3, v2 offset:swizzle(SWAP,16)
	s_waitcnt lgkmcnt(0)
	v_add_f32_e32 v2, v2, v3
	v_mov_b32_e32 v3, v2
	s_nop 1
	v_permlane32_swap_b32_e32 v2, v3
	v_add_f32_e32 v6, v2, v3
	v_mad_i64_i32 v[2:3], s[4:5], s22, v205, v[116:117]
	global_load_ushort v2, v[2:3], off offset:3072
	s_waitcnt vmcnt(0)
	v_lshlrev_b32_e32 v3, 16, v2
	v_fmamk_f32 v2, v6, 0x3c800000, v193
	v_cmp_gt_f32_e32 vcc, s41, v2
	v_mul_f32_e32 v6, 0x4f800000, v2
	s_nop 0
	v_cndmask_b32_e32 v2, v2, v6, vcc
	v_sqrt_f32_e32 v6, v2
	s_nop 0
	v_add_u32_e32 v7, -1, v6
	v_fma_f32 v8, -v7, v6, v2
	v_cmp_ge_f32_e64 s[4:5], 0, v8
	v_add_u32_e32 v8, 1, v6
	s_nop 0
	v_cndmask_b32_e64 v7, v6, v7, s[4:5]
	v_fma_f32 v6, -v8, v6, v2
	v_cmp_lt_f32_e64 s[4:5], 0, v6
	s_nop 1
	v_cndmask_b32_e64 v6, v7, v8, s[4:5]
	v_mul_f32_e32 v7, 0x37800000, v6
	v_cndmask_b32_e32 v6, v6, v7, vcc
	v_cmp_class_f32_e32 vcc, v2, v202
	s_nop 1
	v_cndmask_b32_e32 v2, v6, v2, vcc
	v_div_scale_f32 v6, s[4:5], v2, v2, 1.0
	v_rcp_f32_e32 v7, v6
	s_lshl_b64 s[4:5], s[22:23], 11
	v_fma_f32 v8, -v6, v7, 1.0
	v_fmac_f32_e32 v7, v8, v7
	v_div_scale_f32 v8, vcc, 1.0, v2, 1.0
	v_mul_f32_e32 v9, v8, v7
	v_fma_f32 v10, -v6, v9, v8
	v_fmac_f32_e32 v9, v10, v7
	v_fma_f32 v6, -v6, v9, v8
	v_div_fmas_f32 v6, v6, v7, v9
	v_div_fixup_f32 v2, v6, v2, 1.0
	v_mul_f32_e32 v2, v5, v2
	v_mul_f32_e32 v5, 0xbfb8aa3b, v3
	v_exp_f32_e32 v5, v5
	s_nop 0
	v_add_f32_e32 v5, 1.0, v5
	v_rcp_f32_e32 v99, v5
	s_nop 0
	v_pk_mul_f32 v[2:3], v[98:99], v[2:3]
	s_nop 0
	v_mul_f32_e32 v2, v2, v3
	v_cvt_pk_bf16_f32 v5, v2, s0
	v_lshl_add_u64 v[2:3], v[112:113], 0, s[4:5]
	global_store_short v[2:3], v5, off
	v_add_u32_e32 v5, 0x14200, v4
	ds_read2st64_b32 v[2:3], v4 offset0:34 offset1:35
	ds_read_b32 v5, v5
	s_waitcnt lgkmcnt(0)
; __device__ __forceinline__ float bf2f(unsigned v) { return __uint_as_float(v << 16); }
; __device__ __forceinline__ unsigned f2bf(float f) { return pk2(f, 0.f) & 0xffffu; }
; __device__ __forceinline__ float siluf_(float x) { return x * __builtin_amdgcn_rcpf(1.0f + __builtin_amdgcn_exp2f(-1.4426950408889634f * x)); }
; __device__ __forceinline__ void hgrn_out_phase(const Ctx& F, const Args& a, int l) {
;     ...
;     for (int it0 = 4 * F.bid; it0 < NCHUNK * 4; it0 += 4 * F.G) {
;     ...
; #pragma unroll 4
;             for (int k = 0; k < 32; ++k) {
;                 const int tt = 32 * dir + k;
;                 const float ot = ob_f[tt * 64 + lane] + ob_b[tt * 64 + lane];
;                 const float ss = wave_sum(ot * ot);
;                 const float gg = bf2f(PB[(size_t)(rb + tt) * INW + C_BG + head * 64 + lane]);
;                 const float y = ot * (1.0f / sqrtf(ss * (1.f / 64.f) + EPSN)) * og * siluf_(gg);
;                 Y[(size_t)(rb + tt) * D + 256 + head * 64 + lane] = (bf16_t)f2bf(y);
;             }
;         }
;         __syncthreads();
;     }
	v_add_f32_e32 v2, v2, v5
	v_mul_f32_e32 v5, v2, v2
	ds_swizzle_b32 v5, v5 offset:swizzle(SWAP,1)
	s_waitcnt lgkmcnt(0)
	v_fmac_f32_e32 v5, v2, v2
	ds_swizzle_b32 v6, v5 offset:swizzle(SWAP,2)
	s_waitcnt lgkmcnt(0)
	v_add_f32_e32 v5, v5, v6
	ds_swizzle_b32 v6, v5 offset:swizzle(SWAP,4)
	s_waitcnt lgkmcnt(0)
	v_add_f32_e32 v5, v5, v6
	ds_swizzle_b32 v6, v5 offset:swizzle(SWAP,8)
	s_waitcnt lgkmcnt(0)
	v_add_f32_e32 v5, v5, v6
	ds_swizzle_b32 v6, v5 offset:swizzle(SWAP,16)
	s_waitcnt lgkmcnt(0)
	v_add_f32_e32 v5, v5, v6
	v_mov_b32_e32 v6, v5
	s_nop 1
	v_permlane32_swap_b32_e32 v5, v6
	v_add_f32_e32 v5, v5, v6
	v_mad_i64_i32 v[6:7], s[4:5], s82, v205, v[116:117]
	global_load_ushort v6, v[6:7], off offset:3072
	v_fmamk_f32 v5, v5, 0x3c800000, v193
	v_cmp_gt_f32_e32 vcc, s41, v5
	s_waitcnt vmcnt(0)
	v_lshlrev_b32_e32 v7, 16, v6
	v_mul_f32_e32 v6, 0x4f800000, v5
	v_cndmask_b32_e32 v5, v5, v6, vcc
	v_sqrt_f32_e32 v6, v5
	s_nop 0
	v_add_u32_e32 v8, -1, v6
	v_fma_f32 v9, -v8, v6, v5
	v_cmp_ge_f32_e64 s[4:5], 0, v9
	v_add_u32_e32 v9, 1, v6
	s_nop 0
	v_cndmask_b32_e64 v8, v6, v8, s[4:5]
	v_fma_f32 v6, -v9, v6, v5
	v_cmp_lt_f32_e64 s[4:5], 0, v6
	s_nop 1
	v_cndmask_b32_e64 v6, v8, v9, s[4:5]
	v_mul_f32_e32 v8, 0x37800000, v6
	v_cndmask_b32_e32 v6, v6, v8, vcc
	v_cmp_class_f32_e32 vcc, v5, v202
	s_nop 1
	v_cndmask_b32_e32 v5, v6, v5, vcc
	v_div_scale_f32 v6, s[4:5], v5, v5, 1.0
	v_rcp_f32_e32 v8, v6
	s_lshl_b64 s[4:5], s[82:83], 11
	v_fma_f32 v9, -v6, v8, 1.0
	v_fmac_f32_e32 v8, v9, v8
	v_div_scale_f32 v9, vcc, 1.0, v5, 1.0
	v_mul_f32_e32 v10, v9, v8
	v_fma_f32 v11, -v6, v10, v9
	v_fmac_f32_e32 v10, v11, v8
	v_fma_f32 v6, -v6, v10, v9
	v_div_fmas_f32 v6, v6, v8, v10
	v_div_fixup_f32 v5, v6, v5, 1.0
	v_mul_f32_e32 v6, v2, v5
	v_mul_f32_e32 v2, 0xbfb8aa3b, v7
	v_exp_f32_e32 v2, v2
	s_nop 0
	v_add_f32_e32 v2, 1.0, v2
	v_rcp_f32_e32 v99, v2
	s_nop 0
	v_pk_mul_f32 v[6:7], v[98:99], v[6:7]
	s_nop 0
	v_mul_f32_e32 v2, v6, v7
	v_cvt_pk_bf16_f32 v2, v2, s0
	v_lshl_add_u64 v[6:7], v[112:113], 0, s[4:5]
	global_store_short v[6:7], v2, off
	v_add_u32_e32 v2, 0x14300, v4
	ds_read_b32 v2, v2
	s_waitcnt lgkmcnt(0)
	v_add_f32_e32 v2, v3, v2
	v_mul_f32_e32 v3, v2, v2
	ds_swizzle_b32 v3, v3 offset:swizzle(SWAP,1)
	s_waitcnt lgkmcnt(0)
	v_fmac_f32_e32 v3, v2, v2
	ds_swizzle_b32 v4, v3 offset:swizzle(SWAP,2)
	s_waitcnt lgkmcnt(0)
	v_add_f32_e32 v3, v3, v4
	ds_swizzle_b32 v4, v3 offset:swizzle(SWAP,4)
	s_waitcnt lgkmcnt(0)
	v_add_f32_e32 v3, v3, v4
	ds_swizzle_b32 v4, v3 offset:swizzle(SWAP,8)
	s_waitcnt lgkmcnt(0)
	v_add_f32_e32 v3, v3, v4
	ds_swizzle_b32 v4, v3 offset:swizzle(SWAP,16)
	s_waitcnt lgkmcnt(0)
	v_add_f32_e32 v3, v3, v4
	v_mov_b32_e32 v4, v3
	s_nop 1
	v_permlane32_swap_b32_e32 v3, v4
	v_add_f32_e32 v6, v3, v4
	v_mad_i64_i32 v[4:5], s[4:5], s44, v205, v[116:117]
	global_load_ushort v3, v[4:5], off offset:3072
	v_fmamk_f32 v4, v6, 0x3c800000, v193
	v_cmp_gt_f32_e32 vcc, s41, v4
	v_mul_f32_e32 v5, 0x4f800000, v4
	s_waitcnt vmcnt(0)
	v_lshlrev_b32_e32 v3, 16, v3
	v_cndmask_b32_e32 v4, v4, v5, vcc
	v_sqrt_f32_e32 v5, v4
	s_nop 0
	v_add_u32_e32 v6, -1, v5
	v_fma_f32 v7, -v6, v5, v4
	v_cmp_ge_f32_e64 s[4:5], 0, v7
	v_add_u32_e32 v7, 1, v5
	s_nop 0
	v_cndmask_b32_e64 v6, v5, v6, s[4:5]
	v_fma_f32 v5, -v7, v5, v4
	v_cmp_lt_f32_e64 s[4:5], 0, v5
	s_nop 1
	v_cndmask_b32_e64 v5, v6, v7, s[4:5]
	v_mul_f32_e32 v6, 0x37800000, v5
	v_cndmask_b32_e32 v5, v5, v6, vcc
	v_cmp_class_f32_e32 vcc, v4, v202
	s_nop 1
	v_cndmask_b32_e32 v4, v5, v4, vcc
	v_div_scale_f32 v5, s[4:5], v4, v4, 1.0
	v_rcp_f32_e32 v6, v5
	s_lshl_b64 s[4:5], s[44:45], 11
	s_add_i32 s44, s44, 4
	s_cmp_eq_u32 s6, 0
	v_fma_f32 v7, -v5, v6, 1.0
	v_fmac_f32_e32 v6, v7, v6
	v_div_scale_f32 v7, vcc, 1.0, v4, 1.0
	v_mul_f32_e32 v8, v7, v6
	v_fma_f32 v9, -v5, v8, v7
	v_fmac_f32_e32 v8, v9, v6
	v_fma_f32 v5, -v5, v8, v7
	v_div_fmas_f32 v5, v5, v6, v8
	v_div_fixup_f32 v4, v5, v4, 1.0
	v_mul_f32_e32 v2, v2, v4
	v_mul_f32_e32 v4, 0xbfb8aa3b, v3
	v_exp_f32_e32 v4, v4
	s_nop 0
	v_add_f32_e32 v4, 1.0, v4
	v_rcp_f32_e32 v99, v4
	s_nop 0
	v_pk_mul_f32 v[2:3], v[98:99], v[2:3]
	s_nop 0
	v_mul_f32_e32 v2, v2, v3
	v_cvt_pk_bf16_f32 v4, v2, s0
	v_lshl_add_u64 v[2:3], v[112:113], 0, s[4:5]
	global_store_short v[2:3], v4, off
	s_cbranch_scc0 .LBB0_314
	s_addk_i32 s84, 0x270
	s_nop 0
	s_addk_i32 s85, 0x2700
	s_nop 0
	v_readlane_b32 s66, v253, 19
	v_readlane_b32 s46, v253, 24
	v_readlane_b32 s52, v253, 26
	s_sub_i32 s2, s84, 0x400
	s_cmp_gt_u32 s2, 15
	s_mov_b32 s93, 0xff61b1e6
	s_mov_b32 s94, 0xc2ce8ed0
	s_mov_b32 s95, 0x42b17218
	s_mov_b32 s36, 0x3fb8aa3b
	v_readlane_b32 s67, v253, 20
	v_readlane_b32 s47, v253, 25
	v_readlane_b32 s53, v253, 27
	s_barrier
	s_cbranch_scc0 .LBB0_313

; __device__ __forceinline__ void small_attn_phase(const Ctx& F, const Args& a, int l, int rep) {
;     ...
;     for (int it = (nscan ? F.bid - nwork : F.bid); rep == 0 && it >= 0 && it < 64; it += (nscan ? 64 : F.G)) {
;         const int dh = it >> 3, dblk = it & 7, d = dblk * 8 + (F.tid >> 6), v = F.tid & 63;
;         float S = 0.f;
;         for (int c0 = 0; c0 < NCHUNK; c0 += 20) {
;             float gq[20], aq[20];
; #pragma unroll
;             for (int j = 0; j < 20; ++j) { const size_t u = (size_t)((dh >> 2) * NCHUNK + c0 + j) * 4 + (dh & 3); gq[j] = GS[u * 4096 + d * 64 + v]; aq[j] = HA[u * 64 + d]; }
; #pragma unroll
;             for (int j = 0; j < 20; ++j) { const size_t u = (size_t)((dh >> 2) * NCHUNK + c0 + j) * 4 + (dh & 3); GS[u * 4096 + d * 64 + v] = S; S = aq[j] * S + gq[j]; }
;         }
.LBB0_324:
	s_add_i32 s38, s7, s25
	s_lshl_b64 s[4:5], s[38:39], 14
	v_lshl_add_u64 v[8:9], v[4:5], 0, s[4:5]
	s_lshl_b64 s[4:5], s[38:39], 8
	s_add_i32 s20, s7, s24
	v_lshl_add_u64 v[10:11], v[6:7], 0, s[4:5]
	s_or_b32 s4, s20, 4
	s_mov_b32 s5, s39
	s_lshl_b64 s[22:23], s[4:5], 14
	s_lshl_b64 s[4:5], s[4:5], 8
	v_lshl_add_u64 v[12:13], v[6:7], 0, s[4:5]
	s_add_i32 s4, s38, 8
	s_mov_b32 s5, s39
	global_load_dword v47, v[8:9], off
	global_load_dword v48, v[10:11], off
	global_load_dword v50, v[12:13], off
	v_lshl_add_u64 v[10:11], v[4:5], 0, s[22:23]
	s_lshl_b64 s[22:23], s[4:5], 14
	s_lshl_b64 s[4:5], s[4:5], 8
	v_lshl_add_u64 v[14:15], v[6:7], 0, s[4:5]
	s_or_b32 s4, s20, 12
	s_mov_b32 s5, s39
	v_lshl_add_u64 v[12:13], v[4:5], 0, s[22:23]
	s_lshl_b64 s[22:23], s[4:5], 14
	s_lshl_b64 s[4:5], s[4:5], 8
	v_lshl_add_u64 v[16:17], v[6:7], 0, s[4:5]
	s_add_i32 s4, s38, 16
	s_mov_b32 s5, s39
	global_load_dword v49, v[10:11], off
	global_load_dword v51, v[12:13], off
	global_load_dword v52, v[14:15], off
	global_load_dword v54, v[16:17], off
	v_lshl_add_u64 v[14:15], v[4:5], 0, s[22:23]
	s_lshl_b64 s[22:23], s[4:5], 14
	s_lshl_b64 s[4:5], s[4:5], 8
	v_lshl_add_u64 v[18:19], v[6:7], 0, s[4:5]
	s_add_i32 s4, s7, s26
	s_mov_b32 s5, s39
	v_lshl_add_u64 v[16:17], v[4:5], 0, s[22:23]
	s_lshl_b64 s[22:23], s[4:5], 14
	s_lshl_b64 s[4:5], s[4:5], 8
	v_lshl_add_u64 v[20:21], v[6:7], 0, s[4:5]
	s_add_i32 s4, s38, 24
	s_mov_b32 s5, s39
	global_load_dword v53, v[14:15], off
	global_load_dword v55, v[16:17], off
	global_load_dword v56, v[18:19], off
	global_load_dword v58, v[20:21], off
	v_lshl_add_u64 v[18:19], v[4:5], 0, s[22:23]
	s_lshl_b64 s[22:23], s[4:5], 14
	s_lshl_b64 s[4:5], s[4:5], 8
	v_lshl_add_u64 v[22:23], v[6:7], 0, s[4:5]
	s_add_i32 s4, s7, s27
	s_mov_b32 s5, s39
	v_lshl_add_u64 v[20:21], v[4:5], 0, s[22:23]
	s_lshl_b64 s[22:23], s[4:5], 14
	s_lshl_b64 s[4:5], s[4:5], 8
	v_lshl_add_u64 v[24:25], v[6:7], 0, s[4:5]
	s_add_i32 s4, s38, 32
	s_mov_b32 s5, s39
	global_load_dword v57, v[18:19], off
	global_load_dword v59, v[20:21], off
	global_load_dword v60, v[22:23], off
	global_load_dword v62, v[24:25], off
	v_lshl_add_u64 v[22:23], v[4:5], 0, s[22:23]
	s_lshl_b64 s[22:23], s[4:5], 14
	s_lshl_b64 s[4:5], s[4:5], 8
	v_lshl_add_u64 v[26:27], v[6:7], 0, s[4:5]
	s_add_i32 s4, s7, s28
	s_mov_b32 s5, s39
	v_lshl_add_u64 v[24:25], v[4:5], 0, s[22:23]
	s_lshl_b64 s[22:23], s[4:5], 14
	s_lshl_b64 s[4:5], s[4:5], 8
	v_lshl_add_u64 v[28:29], v[6:7], 0, s[4:5]
	s_add_i32 s4, s38, 40
	s_mov_b32 s5, s39
	global_load_dword v61, v[22:23], off
	global_load_dword v63, v[24:25], off
	global_load_dword v64, v[26:27], off
	global_load_dword v66, v[28:29], off
	v_lshl_add_u64 v[26:27], v[4:5], 0, s[22:23]
	s_lshl_b64 s[22:23], s[4:5], 14
	s_lshl_b64 s[4:5], s[4:5], 8
	v_lshl_add_u64 v[30:31], v[6:7], 0, s[4:5]
	s_add_i32 s4, s7, s29
	s_mov_b32 s5, s39
	v_lshl_add_u64 v[28:29], v[4:5], 0, s[22:23]
	s_lshl_b64 s[22:23], s[4:5], 14
	s_lshl_b64 s[4:5], s[4:5], 8
	v_lshl_add_u64 v[32:33], v[6:7], 0, s[4:5]
	s_add_i32 s4, s38, 48
	s_mov_b32 s5, s39
	global_load_dword v65, v[26:27], off
	global_load_dword v67, v[28:29], off
	global_load_dword v68, v[30:31], off
	global_load_dword v70, v[32:33], off
	v_lshl_add_u64 v[30:31], v[4:5], 0, s[22:23]
	s_lshl_b64 s[22:23], s[4:5], 14
	s_lshl_b64 s[4:5], s[4:5], 8
	v_lshl_add_u64 v[34:35], v[6:7], 0, s[4:5]
	s_add_i32 s4, s7, s33
	s_mov_b32 s5, s39
	v_lshl_add_u64 v[32:33], v[4:5], 0, s[22:23]
	s_lshl_b64 s[22:23], s[4:5], 14
	s_lshl_b64 s[4:5], s[4:5], 8
	v_lshl_add_u64 v[36:37], v[6:7], 0, s[4:5]
	s_add_i32 s4, s38, 56
	s_mov_b32 s5, s39
	global_load_dword v69, v[30:31], off
	global_load_dword v71, v[32:33], off
	global_load_dword v72, v[34:35], off
	global_load_dword v74, v[36:37], off
	v_lshl_add_u64 v[34:35], v[4:5], 0, s[22:23]
	s_lshl_b64 s[22:23], s[4:5], 14
	s_lshl_b64 s[4:5], s[4:5], 8
	v_lshl_add_u64 v[38:39], v[6:7], 0, s[4:5]
	s_add_i32 s4, s7, s36
	s_mov_b32 s5, s39
	v_lshl_add_u64 v[36:37], v[4:5], 0, s[22:23]
	s_lshl_b64 s[22:23], s[4:5], 14
	s_lshl_b64 s[4:5], s[4:5], 8
	v_lshl_add_u64 v[40:41], v[6:7], 0, s[4:5]
	s_add_i32 s4, s38, 64
	s_mov_b32 s5, s39
	global_load_dword v73, v[34:35], off
	global_load_dword v75, v[36:37], off
	global_load_dword v76, v[38:39], off
	global_load_dword v78, v[40:41], off
	v_lshl_add_u64 v[38:39], v[4:5], 0, s[22:23]
	s_lshl_b64 s[22:23], s[4:5], 14
	s_lshl_b64 s[4:5], s[4:5], 8
	v_lshl_add_u64 v[42:43], v[6:7], 0, s[4:5]
	s_add_i32 s4, s7, s37
	s_mov_b32 s5, s39
	v_lshl_add_u64 v[40:41], v[4:5], 0, s[22:23]
	s_lshl_b64 s[22:23], s[4:5], 14
	s_lshl_b64 s[4:5], s[4:5], 8
	s_addk_i32 s38, 0x48
	v_lshl_add_u64 v[44:45], v[6:7], 0, s[4:5]
	s_lshl_b64 s[4:5], s[38:39], 14
	global_load_dword v77, v[38:39], off
	global_load_dword v79, v[40:41], off
	global_load_dword v80, v[42:43], off
	global_load_dword v87, v[44:45], off
	v_lshl_add_u64 v[44:45], v[4:5], 0, s[4:5]
	s_lshl_b64 s[4:5], s[38:39], 8
	s_add_i32 s38, s7, s42
	v_lshl_add_u64 v[42:43], v[4:5], 0, s[22:23]
	s_waitcnt vmcnt(0)
	v_lshl_add_u64 v[82:83], v[6:7], 0, s[4:5]
	s_lshl_b64 s[4:5], s[38:39], 14
	global_load_dword v86, v[42:43], off
	global_load_dword v88, v[44:45], off
	global_load_dword v89, v[82:83], off
	v_lshl_add_u64 v[82:83], v[4:5], 0, s[4:5]
	s_lshl_b64 s[4:5], s[38:39], 8
	v_lshl_add_u64 v[84:85], v[6:7], 0, s[4:5]
	global_load_dword v81, v[82:83], off
	s_waitcnt vmcnt(37)
	v_fmac_f32_e32 v47, v0, v48
	global_load_dword v84, v[84:85], off
	s_waitcnt vmcnt(36)
	v_fmac_f32_e32 v49, v47, v50
	s_waitcnt vmcnt(34)
	v_fmac_f32_e32 v51, v49, v52
	s_waitcnt vmcnt(32)
	v_fmac_f32_e32 v53, v51, v54
	s_waitcnt vmcnt(30)
; __device__ __forceinline__ void small_attn_phase(const Ctx& F, const Args& a, int l, int rep) {
;     ...
;     for (int it = (nscan ? F.bid - nwork : F.bid); rep == 0 && it >= 0 && it < 64; it += (nscan ? 64 : F.G)) {
;         const int dh = it >> 3, dblk = it & 7, d = dblk * 8 + (F.tid >> 6), v = F.tid & 63;
;         float S = 0.f;
;         for (int c0 = 0; c0 < NCHUNK; c0 += 20) {
;             float gq[20], aq[20];
; #pragma unroll
;             for (int j = 0; j < 20; ++j) { const size_t u = (size_t)((dh >> 2) * NCHUNK + c0 + j) * 4 + (dh & 3); gq[j] = GS[u * 4096 + d * 64 + v]; aq[j] = HA[u * 64 + d]; }
; #pragma unroll
;             for (int j = 0; j < 20; ++j) { const size_t u = (size_t)((dh >> 2) * NCHUNK + c0 + j) * 4 + (dh & 3); GS[u * 4096 + d * 64 + v] = S; S = aq[j] * S + gq[j]; }
;         }
;     }
;     if (nscan && F.bid >= nwork) return;
;     for (int u = F.bid; u < 256 + 8; u += nwork) {
	v_fmac_f32_e32 v55, v53, v56
	s_waitcnt vmcnt(28)
	v_fmac_f32_e32 v57, v55, v58
	s_waitcnt vmcnt(26)
	v_fmac_f32_e32 v59, v57, v60
	s_waitcnt vmcnt(24)
	v_fmac_f32_e32 v61, v59, v62
	s_waitcnt vmcnt(22)
	v_fmac_f32_e32 v63, v61, v64
	s_add_i32 s43, s43, 20
	s_addk_i32 s24, 0x50
	s_addk_i32 s42, 0x50
	s_addk_i32 s25, 0x50
	s_addk_i32 s37, 0x50
	s_waitcnt vmcnt(20)
	v_fmac_f32_e32 v65, v63, v66
	s_addk_i32 s36, 0x50
	s_waitcnt vmcnt(18)
	v_fmac_f32_e32 v67, v65, v68
	s_addk_i32 s33, 0x50
	s_addk_i32 s29, 0x50
	s_addk_i32 s28, 0x50
	s_addk_i32 s27, 0x50
	s_addk_i32 s26, 0x50
	global_store_dword v[8:9], v0, off
	s_cmpk_gt_u32 s43, 0xef
	global_store_dword v[10:11], v47, off
	global_store_dword v[12:13], v49, off
	global_store_dword v[14:15], v51, off
	global_store_dword v[16:17], v53, off
	global_store_dword v[18:19], v55, off
	global_store_dword v[20:21], v57, off
	s_waitcnt vmcnt(23)
	v_fmac_f32_e32 v69, v67, v70
	global_store_dword v[22:23], v59, off
	s_waitcnt vmcnt(22)
	v_fmac_f32_e32 v71, v69, v72
	global_store_dword v[24:25], v61, off
	global_store_dword v[26:27], v63, off
	global_store_dword v[28:29], v65, off
	global_store_dword v[30:31], v67, off
	global_store_dword v[32:33], v69, off
	global_store_dword v[34:35], v71, off
	s_waitcnt vmcnt(26)
	v_fmac_f32_e32 v73, v71, v74
	global_store_dword v[36:37], v73, off
	s_waitcnt vmcnt(25)
	v_fmac_f32_e32 v75, v73, v76
	global_store_dword v[38:39], v75, off
	s_waitcnt vmcnt(24)
	v_fmac_f32_e32 v77, v75, v78
	global_store_dword v[40:41], v77, off
	s_waitcnt vmcnt(23)
	v_fmac_f32_e32 v79, v77, v80
	global_store_dword v[42:43], v79, off
	s_waitcnt vmcnt(22)
	v_fmac_f32_e32 v86, v79, v87
	global_store_dword v[44:45], v86, off
	s_waitcnt vmcnt(21)
	v_fmac_f32_e32 v88, v86, v89
	global_store_dword v[82:83], v88, off
	s_waitcnt vmcnt(20)
	v_fmac_f32_e32 v81, v88, v84
	v_mov_b32_e32 v0, v81
	s_cbranch_scc0 .LBB0_324
	s_add_i32 s2, s2, s44
	s_cmp_gt_u32 s2, 63
	s_cbranch_scc0 .LBB0_323
	s_waitcnt vmcnt(0)
	s_barrier
	v_readfirstlane_b32 s2, v166
	s_cmp_lg_u32 s2, 0
	s_cbranch_scc1 .LBB0_326
	buffer_wbl2 sc1
	s_waitcnt vmcnt(0)
	s_add_u32 s22, s14, 0x3900
	s_addc_u32 s23, s15, 0
	s_mov_b64 s[4:5], exec
	s_mov_b64 exec, 1
	v_mov_b32_e32 v2, 1
	global_atomic_add v1, v2, s[22:23]
	s_mov_b64 exec, s[4:5]
.LBB0_326:
	s_sub_i32 s2, s60, 0x64
	s_cmp_lt_u32 s2, 4
	s_cbranch_scc1 .LBB0_433
	v_readlane_b32 s2, v251, 10
	s_cmp_lt_i32 s60, s2
	v_readlane_b32 s22, v251, 8
	s_cselect_b64 s[4:5], -1, 0
	v_readlane_b32 s23, v251, 9
	s_or_b64 s[4:5], s[22:23], s[4:5]
	s_cmpk_lt_i32 s60, 0x108
	s_cselect_b64 s[22:23], -1, 0
	s_and_b64 s[4:5], s[4:5], s[22:23]
	s_andn2_b64 vcc, exec, s[4:5]
	s_movk_i32 s29, 0xffd0
	s_cbranch_vccnz .LBB0_433
; #define LAS __attribute__((address_space(3)))
; template <bool NA> ...
;     const int lane = tid & 63, q = lane & 31, h = lane >> 5;
;     constexpr int KB = 9216, VB = 9216, VOFF = 2 * KB, BOFF = VOFF + 2 * VB;
;     LAS float* biasL = (LAS float*)(lds + BOFF);
;     bf16x8 qb[4];
;     { const bf16_t* qp = PB + (size_t)(q_tok0 + q) * INW + qcol + 8 * h;
; #pragma unroll
;       for (int s = 0; s < 4; ++s) qb[s] = *(const bf16x8*)(qp + 16 * s); }
;     __syncthreads();
;     if (NA) { for (int i = tid; i < 465; i += 512) biasL[i] = relb[i] * LOG2E; }
;     f32x16 o0, o1, negm;
; #pragma unroll
;     for (int r = 0; r < 16; ++r) { o0[r] = 0.f; o1[r] = 0.f; negm[r] = 0.f; }
;     float m = 0.f, l = 0.f;
;     const int srow = tid >> 3, sch = tid & 7;
;     u32x4 kreg, vreg;
;     { const int t0 = SEQ;
;       kreg = *(const u32x4*)(PB + (size_t)(t0 + srow) * INW + kcol + 8 * sch); vreg = *(const u32x4*)(VT + (size_t)srow * NTOK + t0 + 8 * sch); }
;     *(LAS u32x4*)(lds + srow * 144 + sch * 16) = kreg;
;     { LAS unsigned char* vp = lds + VOFF + srow * 144 + (sch >> 1) * 32 + (sch & 1) * 8;
;       *(LAS u32x2*)vp = (u32x2){vreg.x, vreg.y}; *(LAS u32x2*)(vp + 16) = (u32x2){vreg.z, vreg.w}; }
;     __syncthreads();
;     const int na_cs = NA ? min(max(na_qc0 + q - 8, 0), 48) : 0;
;     const int na_rs = NA ? min(max(na_r - 4, 0), 248) : 0;
; __device__ __forceinline__ void small_attn_phase(const Ctx& F, const Args& a, int l, int rep) {
;     ...
;     for (int u = F.bid; u < 256 + 8; u += nwork) {
;         if (u < 256) {
;             const int head = u & 3, rg = u >> 2, r = 4 * rg + (w >> 1);
;             const int rs0 = min(max(4 * rg - 4, 0), 248), rs3 = min(max(4 * rg + 3 - 4, 0), 248);
;             attn_unit<true>(F.lds, PB, VTD + (size_t)head * 64 * NTOK, Y, 64 * r + 32 * (w & 1), C_DQ + 64 * head, C_DK + 64 * head, 768 + 64 * head, 4 + (rs3 + 8 - rs0), 64 * rs0,
;                             ATT_SCALE * LOG2E, r, rs0, 32 * (w & 1), in_ptr(18) + ((size_t)l * 4 + head) * 465, F.tid);
	v_readlane_b32 s24, v253, 9
	v_readlane_b32 s25, v253, 10
	s_lshl_b64 s[4:5], s[24:25], 2
	s_ashr_i32 s2, s6, 6
	v_writelane_b32 v253, s4, 31
	s_ashr_i32 s8, s6, 7
	v_readlane_b32 s6, v252, 61
	v_writelane_b32 v253, s5, 32
	s_lshl_b32 s4, s2, 5
	s_add_i32 s5, s4, 0x4000
	v_and_b32_e32 v6, 31, v168
	v_readlane_b32 s7, v252, 62
	s_lshl_b32 s2, s2, 4
	v_or_b32_e32 v2, s5, v6
	v_mov_b64_e32 v[4:5], s[6:7]
	s_and_b32 s20, s4, 0x60
	s_and_b32 s57, s2, 0xffffffc0
	s_and_b32 s2, s4, 32
	v_mad_i64_i32 v[170:171], s[4:5], v2, s21, v[4:5]
	s_movk_i32 s4, 0x1d1
	s_nop 0
	v_cmp_gt_i32_e64 s[4:5], s4, v168
	v_ashrrev_i32_e32 v167, 3, v168
	v_add_u32_e32 v8, 0x4000, v167
	v_writelane_b32 v253, s4, 33
	v_and_b32_e32 v0, 7, v168
	v_lshlrev_b32_e32 v174, 3, v0
	v_writelane_b32 v253, s5, 34
	v_mad_i64_i32 v[4:5], s[4:5], v8, s21, v[4:5]
	v_readlane_b32 s4, v251, 25
	v_lshlrev_b32_e32 v0, 4, v0
	v_readlane_b32 s5, v251, 26
	v_lshl_add_u64 v[176:177], v[4:5], 0, v[0:1]
	s_mov_b32 s22, 0x8200
	v_mov_b64_e32 v[4:5], s[4:5]
	v_mad_i64_i32 v[178:179], s[4:5], v167, s22, v[4:5]
	s_movk_i32 s4, 0x90
	s_nop 0
	v_mul_lo_u32 v4, v167, s4
	v_lshlrev_b32_e32 v8, 3, v168
	v_bfe_u32 v7, v168, 5, 1
	v_add_u32_e32 v4, 0, v4
	v_and_b32_e32 v5, 0x60, v0
	v_and_b32_e32 v8, 8, v8
	v_lshlrev_b32_e32 v172, 3, v7
	v_add_u32_e32 v173, v4, v0
	v_add3_u32 v175, v4, v5, v8
	v_lshl_add_u64 v[180:181], s[6:7], 0, v[0:1]
	v_lshlrev_b32_e32 v5, 4, v7
	v_lshlrev_b32_e32 v0, 2, v7
	v_add_u32_e32 v7, 0x4040, v167
	v_mad_i64_i32 v[182:183], s[4:5], v7, s21, 0
	v_ashrrev_i32_e32 v3, 31, v2
	v_readlane_b32 s4, v251, 12
	v_lshlrev_b64 v[2:3], 11, v[2:3]
	v_readlane_b32 s5, v251, 13
	v_or_b32_e32 v218, s2, v6
	v_mul_u32_u24_e32 v4, 0x90, v6
	v_lshl_add_u64 v[184:185], s[4:5], 0, v[2:3]
	v_readlane_b32 s4, v251, 18
	v_readlane_b32 s5, v251, 19
	v_add3_u32 v217, 0, v4, v5
	v_or_b32_e32 v4, 32, v0
	v_mov_b64_e32 v[2:3], s[4:5]
	v_mad_i64_i32 v[186:187], s[4:5], v167, s22, v[2:3]
	v_add_u32_e32 v2, 0x4080, v167
	v_mad_i64_i32 v[188:189], s[4:5], v2, s21, 0
	v_add_u32_e32 v2, 0x40c0, v167
	v_mad_i64_i32 v[190:191], s[4:5], v2, s21, 0
	v_sub_u32_e64 v2, v218, 8 clamp
	v_min_u32_e32 v2, 48, v2
	v_cmp_ge_u32_e64 s[4:5], v0, v2
	v_add_u32_e32 v3, 16, v2
	v_cmp_lt_u32_e64 s[6:7], v4, v3
	v_writelane_b32 v253, s4, 29
	v_cmp_lt_u32_e32 vcc, v0, v2
	v_lshlrev_b32_e32 v222, 2, v168
	v_writelane_b32 v253, s5, 30
	v_cmp_ge_u32_e64 s[4:5], v4, v2
	v_or_b32_e32 v4, 1, v0
	s_and_b64 s[50:51], s[4:5], s[6:7]
	v_cmp_ge_u32_e64 s[4:5], v4, v2
	v_or_b32_e32 v4, 33, v0
	v_cmp_lt_u32_e64 s[6:7], v4, v3
	v_writelane_b32 v253, s4, 35
	v_add_u32_e32 v169, 0x200, v168
	v_or_b32_e32 v221, s20, v6
	v_writelane_b32 v253, s5, 36
	v_cmp_ge_u32_e64 s[4:5], v4, v2
	v_or_b32_e32 v4, 2, v0
	s_and_b64 s[54:55], s[4:5], s[6:7]
	v_cmp_ge_u32_e64 s[4:5], v4, v2
	v_or_b32_e32 v4, 34, v0
	v_cmp_lt_u32_e64 s[6:7], v4, v3
	v_writelane_b32 v253, s4, 37
	s_add_i32 s52, s60, 0xfffffefc
	s_mov_b32 s43, s8
	v_writelane_b32 v253, s5, 38
	v_cmp_ge_u32_e64 s[4:5], v4, v2
	v_or_b32_e32 v4, 3, v0
	s_and_b64 s[58:59], s[4:5], s[6:7]
	v_cmp_ge_u32_e64 s[4:5], v4, v2
	v_or_b32_e32 v4, 35, v0
	v_cmp_lt_u32_e64 s[6:7], v4, v3
	v_writelane_b32 v253, s4, 39
	v_lshlrev_b32_e32 v194, 1, v0
	s_mov_b32 s53, s60
	v_writelane_b32 v253, s5, 40
	v_cmp_ge_u32_e64 s[4:5], v4, v2
	v_or_b32_e32 v4, 8, v0
	s_and_b64 s[62:63], s[4:5], s[6:7]
	v_cmp_ge_u32_e64 s[4:5], v4, v2
	v_or_b32_e32 v4, 40, v0
	v_cmp_lt_u32_e64 s[6:7], v4, v3
	v_writelane_b32 v253, s4, 41
	s_mov_b32 s42, s60
	s_nop 0
	v_writelane_b32 v253, s5, 42
	v_cmp_ge_u32_e64 s[4:5], v4, v2
	v_or_b32_e32 v4, 9, v0
	s_and_b64 s[66:67], s[4:5], s[6:7]
	v_cmp_ge_u32_e64 s[4:5], v4, v2
	v_or_b32_e32 v4, 41, v0
	v_cmp_lt_u32_e64 s[6:7], v4, v3
	v_writelane_b32 v253, s4, 43
	s_nop 1
	v_writelane_b32 v253, s5, 44
	v_cmp_ge_u32_e64 s[4:5], v4, v2
	v_or_b32_e32 v4, 10, v0
	s_and_b64 s[70:71], s[4:5], s[6:7]
	v_cmp_ge_u32_e64 s[4:5], v4, v2
	v_or_b32_e32 v4, 42, v0
	v_cmp_lt_u32_e64 s[6:7], v4, v3
	v_writelane_b32 v253, s4, 45
	s_nop 1
	v_writelane_b32 v253, s5, 46
	v_cmp_ge_u32_e64 s[4:5], v4, v2
	v_or_b32_e32 v4, 11, v0
	s_and_b64 s[74:75], s[4:5], s[6:7]
	v_cmp_ge_u32_e64 s[4:5], v4, v2
	v_or_b32_e32 v4, 43, v0
	v_cmp_lt_u32_e64 s[6:7], v4, v3
	v_writelane_b32 v253, s4, 47
	s_nop 1
	v_writelane_b32 v253, s5, 48
	v_cmp_ge_u32_e64 s[4:5], v4, v2
	v_or_b32_e32 v4, 16, v0
	s_and_b64 s[78:79], s[4:5], s[6:7]
	v_cmp_ge_u32_e64 s[4:5], v4, v2
	s_and_b64 s[4:5], s[4:5], vcc
	v_or_b32_e32 v4, 48, v0
	v_writelane_b32 v253, s4, 49
	v_cmp_lt_u32_e64 s[80:81], v4, v3
	v_or_b32_e32 v4, 17, v0
	v_writelane_b32 v253, s5, 50
	v_cmp_ge_u32_e32 vcc, v4, v2
	v_cmp_lt_u32_e64 s[4:5], v4, v3
	s_and_b64 s[4:5], vcc, s[4:5]
	v_or_b32_e32 v4, 49, v0
	v_writelane_b32 v253, s4, 51
	v_cmp_lt_u32_e64 s[82:83], v4, v3
	v_or_b32_e32 v4, 18, v0
	v_writelane_b32 v253, s5, 52
	v_cmp_ge_u32_e32 vcc, v4, v2
	v_cmp_lt_u32_e64 s[4:5], v4, v3
	s_and_b64 s[4:5], vcc, s[4:5]
	v_or_b32_e32 v4, 50, v0
	v_writelane_b32 v253, s4, 53
	v_cmp_lt_u32_e64 s[84:85], v4, v3
	v_or_b32_e32 v4, 19, v0
	v_writelane_b32 v253, s5, 54
	v_cmp_ge_u32_e32 vcc, v4, v2
	v_cmp_lt_u32_e64 s[4:5], v4, v3
	s_and_b64 s[4:5], vcc, s[4:5]
	v_or_b32_e32 v4, 51, v0
	v_writelane_b32 v253, s4, 55
	v_cmp_lt_u32_e64 s[86:87], v4, v3
	v_or_b32_e32 v4, 24, v0
	v_writelane_b32 v253, s5, 56
	v_cmp_ge_u32_e32 vcc, v4, v2
	v_cmp_lt_u32_e64 s[4:5], v4, v3
	v_or_b32_e32 v4, 56, v0
	v_cmp_lt_u32_e64 s[88:89], v4, v3
	v_or_b32_e32 v4, 25, v0
	s_and_b64 s[44:45], vcc, s[4:5]
	v_cmp_ge_u32_e32 vcc, v4, v2
	v_cmp_lt_u32_e64 s[4:5], v4, v3
	v_or_b32_e32 v4, 57, v0
	v_cmp_lt_u32_e64 s[90:91], v4, v3
	v_or_b32_e32 v4, 26, v0
	s_and_b64 s[64:65], vcc, s[4:5]
	v_cmp_ge_u32_e32 vcc, v4, v2
	v_cmp_lt_u32_e64 s[4:5], v4, v3
	v_or_b32_e32 v4, 58, v0
	v_cmp_lt_u32_e64 s[92:93], v4, v3
	v_or_b32_e32 v4, 27, v0
	s_and_b64 s[68:69], vcc, s[4:5]
	v_cmp_ge_u32_e32 vcc, v4, v2
	v_or_b32_e32 v2, 59, v0
	v_cmp_lt_u32_e64 s[94:95], v2, v3
	v_max_i32_e32 v2, 0xffffffd1, v168
	v_sub_u32_e32 v2, v2, v168
	v_add_u32_e32 v2, 0x1ff, v2
	v_cmp_lt_u32_e64 s[4:5], v4, v3
	v_lshrrev_b32_e32 v3, 9, v2
	s_movk_i32 s6, 0x1ff
	v_add_u32_e32 v3, 1, v3
	v_cmp_lt_u32_e64 s[6:7], s6, v2
	v_and_b32_e32 v219, 0xfffffe, v3
	v_sub_u32_e32 v2, v0, v6
	v_writelane_b32 v253, s6, 57
	s_and_b64 s[4:5], vcc, s[4:5]
	v_lshl_add_u32 v220, v219, 9, v168
	v_writelane_b32 v253, s7, 58
	v_cmp_ne_u32_e64 s[6:7], v3, v219
	v_subrev_u32_e32 v3, s2, v2
	v_lshlrev_b32_e32 v3, 2, v3
	v_writelane_b32 v253, s6, 59
	s_nop 1
	v_writelane_b32 v253, s7, 60
	s_add_i32 s6, 0, 0x9000
	v_writelane_b32 v253, s6, 61
	v_add_u32_e32 v223, s6, v222
	s_mul_hi_i32 s6, s24, 0x1d10
	v_writelane_b32 v253, s6, 62
	s_mul_i32 s6, s24, 0x1d10
	v_writelane_b32 v253, s6, 63
	s_mul_i32 s6, s8, 0x7c
	v_subrev_u32_e32 v3, s6, v3
	v_readlane_b32 s6, v252, 20
	s_nop 1
	v_add_u32_e32 v224, s6, v3
	s_mul_i32 s6, s8, 31
	v_subrev_u32_e32 v2, s6, v2
	v_subrev_u32_e32 v2, s2, v2
	v_add_u32_e32 v192, 0xc6, v2
	s_branch .LBB0_332

; __device__ __forceinline__ unsigned pk2(float lo, float hi) { const f32x2_t v = {lo, hi}; const bf16x2_t b = __builtin_convertvector(v, bf16x2_t); return __builtin_bit_cast(unsigned, b); }
; __device__ __forceinline__ float xor32_sum(float v) { const auto rr = __builtin_amdgcn_permlane32_swap(__float_as_uint(v), __float_as_uint(v), false, false); return __uint_as_float(rr[0]) + __uint_as_float(rr[1]); }
; template <bool NA> ...
;     ...
;     const float lt = xor32_sum(l), inv = 1.0f / lt;
;     bf16_t* yp = Y + (size_t)(q_tok0 + q) * D + ycol + 4 * h;
; #pragma unroll
;     for (int g4 = 0; g4 < 4; ++g4) {
;         u32x2 w0, w1;
;         w0.x = pk2(o0[4 * g4] * inv, o0[4 * g4 + 1] * inv); w0.y = pk2(o0[4 * g4 + 2] * inv, o0[4 * g4 + 3] * inv);
;         w1.x = pk2(o1[4 * g4] * inv, o1[4 * g4 + 1] * inv); w1.y = pk2(o1[4 * g4 + 2] * inv, o1[4 * g4 + 3] * inv);
;         *(u32x2*)(yp + 8 * g4) = w0; *(u32x2*)(yp + 32 + 8 * g4) = w1;
;     }
; __device__ __forceinline__ void small_attn_phase(const Ctx& F, const Args& a, int l, int rep) {
;     ...
;     for (int u = F.bid; u < 256 + 8; u += nwork) {
.LBB0_331:
	v_div_scale_f32 v0, s[6:7], v4, v4, 1.0
	v_rcp_f32_e32 v5, v0
	v_div_scale_f32 v6, vcc, 1.0, v4, 1.0
	v_mov_b32_e32 v195, v1
	v_fma_f32 v7, -v0, v5, 1.0
	v_fmac_f32_e32 v5, v7, v5
	v_mul_f32_e32 v7, v6, v5
	v_fma_f32 v8, -v0, v7, v6
	v_fmac_f32_e32 v7, v8, v5
	v_fma_f32 v0, -v0, v7, v6
	v_div_fmas_f32 v0, v0, v5, v7
	v_div_fixup_f32 v0, v0, v4, 1.0
	v_pk_mul_f32 v[4:5], v[16:17], v[0:1] op_sel_hi:[1,0]
	v_pk_mul_f32 v[6:7], v[18:19], v[0:1] op_sel_hi:[1,0]
	v_cvt_pk_bf16_f32 v4, v4, v5
	v_cvt_pk_bf16_f32 v5, v6, v7
	v_pk_mul_f32 v[6:7], v[0:1], v[32:33] op_sel_hi:[0,1]
	v_pk_mul_f32 v[8:9], v[0:1], v[34:35] op_sel_hi:[0,1]
	v_lshl_add_u64 v[2:3], v[2:3], 0, v[194:195]
	v_cvt_pk_bf16_f32 v6, v6, v7
	v_cvt_pk_bf16_f32 v7, v8, v9
	global_store_dwordx2 v[2:3], v[4:5], off
	global_store_dwordx2 v[2:3], v[6:7], off offset:64
	v_pk_mul_f32 v[4:5], v[20:21], v[0:1] op_sel_hi:[1,0]
	v_pk_mul_f32 v[6:7], v[22:23], v[0:1] op_sel_hi:[1,0]
	v_cvt_pk_bf16_f32 v4, v4, v5
	v_cvt_pk_bf16_f32 v5, v6, v7
	v_pk_mul_f32 v[6:7], v[0:1], v[36:37] op_sel_hi:[0,1]
	v_pk_mul_f32 v[8:9], v[0:1], v[38:39] op_sel_hi:[0,1]
	v_cvt_pk_bf16_f32 v6, v6, v7
	v_cvt_pk_bf16_f32 v7, v8, v9
	global_store_dwordx2 v[2:3], v[4:5], off offset:16
	global_store_dwordx2 v[2:3], v[6:7], off offset:80
	v_pk_mul_f32 v[4:5], v[24:25], v[0:1] op_sel_hi:[1,0]
	v_pk_mul_f32 v[6:7], v[26:27], v[0:1] op_sel_hi:[1,0]
	v_cvt_pk_bf16_f32 v4, v4, v5
	v_cvt_pk_bf16_f32 v5, v6, v7
	v_pk_mul_f32 v[6:7], v[0:1], v[40:41] op_sel_hi:[0,1]
	v_pk_mul_f32 v[8:9], v[0:1], v[42:43] op_sel_hi:[0,1]
	v_cvt_pk_bf16_f32 v6, v6, v7
	v_cvt_pk_bf16_f32 v7, v8, v9
	global_store_dwordx2 v[2:3], v[4:5], off offset:32
	global_store_dwordx2 v[2:3], v[6:7], off offset:96
	v_pk_mul_f32 v[4:5], v[28:29], v[0:1] op_sel_hi:[1,0]
	v_pk_mul_f32 v[6:7], v[30:31], v[0:1] op_sel_hi:[1,0]
	v_readlane_b32 s2, v251, 10
	v_cvt_pk_bf16_f32 v4, v4, v5
	v_cvt_pk_bf16_f32 v5, v6, v7
	v_pk_mul_f32 v[6:7], v[0:1], v[44:45] op_sel_hi:[0,1]
	v_pk_mul_f32 v[8:9], v[0:1], v[46:47] op_sel_hi:[0,1]
	s_sub_i32 s6, s60, 0x48
	s_cmp_lt_u32 s6, 4
	s_cselect_b32 s6, 28, s2
	s_cmp_eq_u32 s42, s60
	s_cselect_b32 s2, s6, s2
	s_add_i32 s42, s42, s2
	s_add_i32 s52, s52, s2
	s_add_i32 s53, s53, s18
	v_cvt_pk_bf16_f32 v6, v6, v7
	v_cvt_pk_bf16_f32 v7, v8, v9
	s_cmpk_gt_i32 s42, 0x107
	global_store_dwordx2 v[2:3], v[4:5], off offset:48
	global_store_dwordx2 v[2:3], v[6:7], off offset:112
	s_cbranch_scc1 .LBB0_433

; __global__ void __launch_bounds__(512, 2) mk_fwd(Args args) {
;     ...
;         if (ph + 1 < args.ph_hi) { if (ph == 0) grid.sync(); else xcd_barrier(xbar); if (PROBE_DBL & 128) xcd_barrier(xbar); }
.LBB0_724:
	s_mov_b32 s2, 0x1200480
	s_mov_b32 s3, 0x120048
	s_bitcmp1_b64 s[2:3], s33
	s_cbranch_scc0 .Lcs_bar
	s_mov_b64 s[4:5], 0
	s_branch .LBB0_778
